# scan: W / QD fragments loaded straight from global into MFMA operand registers one chunk ahead (no LDS image for them, 4 fewer LDS-DMA pieces per wave and chunk)
# baseline (speedup 1.0000x reference)
.LBB0_362:
	v_readlane_b32 s4, v242, 8
	s_waitcnt lgkmcnt(0)
	s_barrier
	v_mbcnt_lo_u32_b32 v0, -1, 0
	v_mbcnt_hi_u32_b32 v0, -1, v0
	v_mov_b32_e32 v30, 0
	s_mov_b32 s4, s40
	s_mov_b32 s5, s77
	v_and_b32_e32 v1, 15, v0
	v_lshrrev_b32_e32 v2, 4, v0
	s_lshr_b32 s38, s5, 1
	s_and_b32 s39, s5, 1
	s_lshr_b32 s7, s4, 2
	s_lshl_b32 s7, s7, 5
	s_and_b32 s8, s4, 3
	s_lshl_b32 s9, s7, 14
	s_add_u32 s10, s92, 0x9000000
	s_addc_u32 s11, s93, 0
	s_add_u32 s10, s10, s9
	s_addc_u32 s11, s11, 0
	s_add_u32 s12, s92, 0xb000000
	s_addc_u32 s13, s93, 0
	s_add_u32 s12, s12, s9
	s_addc_u32 s13, s13, 0
	s_add_u32 s14, s92, 0xd000000
	s_addc_u32 s15, s93, 0
	s_add_u32 s14, s14, s9
	s_addc_u32 s15, s15, 0
	s_lshl_b32 s26, s7, 13
	s_add_u32 s18, s92, 0xf000000
	s_addc_u32 s19, s93, 0
	s_add_u32 s18, s18, s26
	s_addc_u32 s19, s19, 0
	s_add_u32 s24, s90, 0x2000000
	s_addc_u32 s25, s91, 0
	s_add_u32 s24, s24, s9
	s_addc_u32 s25, s25, 0
	s_lshl_b32 s26, s8, 6
	s_add_u32 s24, s24, s26
	s_addc_u32 s25, s25, 0
	s_add_u32 s42, s92, 0x500000
	s_addc_u32 s43, s93, 0
	v_and_b32_e32 v26, 31, v0
	v_add_u32_e32 v26, s7, v26
	v_lshlrev_b32_e32 v26, 2, v26
	global_load_dword v24, v26, s[42:43]
	v_mov_b32_e32 v30, 0
	s_lshl_b32 s30, s5, 11
	s_lshl_b32 s31, s5, 10
	s_and_b32 s32, s5, 3
	s_lshl_b32 s32, s32, 10
	s_lshl_b32 s7, s5, 3
	v_add_u32_e32 v26, s7, v2
	v_and_b32_e32 v27, 15, v26
	v_xor_b32_e32 v27, v27, v1
	v_lshlrev_b32_e32 v27, 4, v27
	v_lshl_add_u32 v3, v26, 8, v27
	s_lshl_b32 s7, s5, 3
	s_add_u32 s7, s7, 4
	v_add_u32_e32 v26, s7, v2
	v_and_b32_e32 v27, 15, v26
	v_xor_b32_e32 v27, v27, v1
	v_lshlrev_b32_e32 v27, 4, v27
	v_lshl_add_u32 v4, v26, 8, v27
	v_lshrrev_b32_e32 v28, 3, v0
	v_and_b32_e32 v29, 7, v0
	s_lshl_b32 s7, s5, 4
	v_add_u32_e32 v26, s7, v28
	v_bfe_u32 v27, v26, 1, 3
	v_xor_b32_e32 v27, v27, v29
	v_lshlrev_b32_e32 v27, 4, v27
	v_lshl_add_u32 v5, v26, 7, v27
	s_lshl_b32 s7, s5, 4
	s_add_u32 s7, s7, 8
	v_add_u32_e32 v26, s7, v28
	v_bfe_u32 v27, v26, 1, 3
	v_xor_b32_e32 v27, v27, v29
	v_lshlrev_b32_e32 v27, 4, v27
	v_lshl_add_u32 v6, v26, 7, v27
	s_lshl_b32 s7, s5, 3
	v_add_u32_e32 v26, s7, v28
	v_bfe_u32 v27, v26, 1, 3
	v_xor_b32_e32 v27, v27, v29
	v_lshlrev_b32_e32 v27, 4, v27
	v_lshl_add_u32 v7, v26, 7, v27
	s_and_b32 s7, s5, 3
	s_lshl_b32 s7, s7, 4
	v_lshrrev_b32_e32 v26, 2, v0
	v_add_u32_e32 v26, s7, v26
	v_and_b32_e32 v27, 3, v0
	v_lshlrev_b32_e32 v27, 4, v27
	v_lshl_add_u32 v8, v26, 8, v27
	s_lshl_b32 s7, s39, 4
	v_add_u32_e32 v26, s7, v1
	s_lshl_b32 s8, s38, 4
	v_add_u32_e32 v27, s8, v1
	v_lshlrev_b32_e32 v28, 4, v2
	s_movk_i32 s9, 0x110
	v_mul_lo_u32 v29, v26, s9
	v_add_u32_e32 v10, v29, v28
	v_add_u32_e32 v10, 0x1c000, v10
	v_lshlrev_b32_e32 v31, 3, v2
	s_lshl_b32 s9, s38, 6
	v_add3_u32 v21, v29, v31, s9
	v_add_u32_e32 v21, 0x1c000, v21
	s_movk_i32 s9, 0x90
	v_mul_lo_u32 v29, v26, s9
	v_add_u32_e32 v19, v29, v28
	v_add_u32_e32 v19, 0x1e200, v19
	s_lshl_b32 s9, s38, 5
	v_add3_u32 v20, v29, v31, s9
	v_add_u32_e32 v20, 0x1e200, v20
	v_lshl_add_u32 v136, v27, 8, v28
	v_add_u32_e32 v29, 0, v2
	v_xor_b32_e32 v29, v29, v1
	v_lshlrev_b32_e32 v29, 4, v29
	v_lshl_add_u32 v11, v27, 8, v29
	v_add_u32_e32 v29, 4, v2
	v_xor_b32_e32 v29, v29, v1
	v_lshlrev_b32_e32 v29, 4, v29
	v_lshl_add_u32 v12, v27, 8, v29
	v_add_u32_e32 v29, 8, v2
	v_xor_b32_e32 v29, v29, v1
	v_lshlrev_b32_e32 v29, 4, v29
	v_lshl_add_u32 v13, v27, 8, v29
	v_add_u32_e32 v29, 12, v2
	v_xor_b32_e32 v29, v29, v1
	v_lshlrev_b32_e32 v29, 4, v29
	v_lshl_add_u32 v14, v27, 8, v29
	v_lshrrev_b32_e32 v31, 1, v1
	s_lshl_b32 s9, s38, 5
	v_add_u32_e32 v26, s9, v1
	v_add_u32_e32 v29, 0, v2
	v_xor_b32_e32 v29, v29, v31
	v_lshlrev_b32_e32 v29, 4, v29
	v_lshl_add_u32 v15, v26, 7, v29
	v_add_u32_e32 v15, 0x10000, v15
	v_lshl_add_u32 v17, v27, 7, v29
	v_add_u32_e32 v17, 0x18000, v17
	v_add_u32_e32 v29, 4, v2
	v_xor_b32_e32 v29, v29, v31
	v_lshlrev_b32_e32 v29, 4, v29
	v_lshl_add_u32 v16, v26, 7, v29
	v_add_u32_e32 v16, 0x10000, v16
	v_lshl_add_u32 v18, v27, 7, v29
	v_add_u32_e32 v18, 0x18000, v18
	s_lshl_b32 s9, s38, 10
	v_lshlrev_b32_e32 v29, 8, v2
	v_add_u32_e32 v29, s9, v29
	s_lshl_b32 s9, s39, 5
	v_lshl_add_u32 v29, v1, 1, v29
	v_add_u32_e32 v29, s9, v29
	v_add_u32_e32 v22, 0x1f400, v29
	v_lshlrev_b32_e32 v29, 3, v2
	v_lshl_add_u32 v29, v27, 8, v29
	v_add_u32_e32 v9, s9, v29
	v_mov_b32_e32 v32, 0
	v_mov_b32_e32 v33, 0
	v_mov_b32_e32 v34, 0
	v_mov_b32_e32 v35, 0
	v_lshl_add_u32 v26, s5, 6, v0
	v_lshlrev_b32_e32 v27, 4, v26
	v_add_u32_e32 v27, 0x1c000, v27
	ds_write_b128 v27, v[32:35]
	v_and_b32_e32 v26, 31, v26
	v_lshlrev_b32_e32 v27, 4, v26
	v_add_u32_e32 v27, 0x1e000, v27
	ds_write_b128 v27, v[32:35]
	v_mov_b32_e32 v92, 0
	v_mov_b32_e32 v93, 0
	v_mov_b32_e32 v94, 0
	v_mov_b32_e32 v95, 0
	v_mov_b32_e32 v96, 0
	v_mov_b32_e32 v97, 0
	v_mov_b32_e32 v98, 0
	v_mov_b32_e32 v99, 0
	s_mov_b32 s6, 0
	s_add_i32 m0, s32, 0x1f400
	s_nop 0
	global_load_lds_dwordx4 v8, s[24:25]
	s_add_i32 m0, s30, 0x10000
	s_nop 0
	global_load_lds_dwordx4 v5, s[14:15]
	s_add_i32 m0, s30, 0x10400
	s_nop 0
	global_load_lds_dwordx4 v6, s[14:15]
	s_add_i32 m0, s31, 0x18000
	s_nop 0
	global_load_lds_dwordx4 v7, s[18:19]
	s_add_u32 s26, s24, 0x4000
	s_addc_u32 s27, s25, 0
	s_add_i32 m0, s32, 0x20400
	s_nop 0
	global_load_lds_dwordx4 v8, s[26:27]
	global_load_dwordx4 v[48:51], v136, s[10:11] offset:0
	global_load_dwordx4 v[52:55], v136, s[10:11] offset:64
	global_load_dwordx4 v[56:59], v136, s[10:11] offset:128
	global_load_dwordx4 v[60:63], v136, s[10:11] offset:192
	global_load_dwordx4 v[64:67], v136, s[12:13] offset:0
	global_load_dwordx4 v[68:71], v136, s[12:13] offset:64
	global_load_dwordx4 v[72:75], v136, s[12:13] offset:128
	global_load_dwordx4 v[76:79], v136, s[12:13] offset:192
	s_waitcnt vmcnt(0) lgkmcnt(0)
	s_barrier
.Lscan_loop:
	s_and_b32 s7, s6, 3
	s_lshl_b32 s7, s7, 12
	v_add_u32_e32 v23, s7, v22
	ds_read_b128 v[32:35], v10 offset:0
	ds_read_b128 v[36:39], v10 offset:64
	ds_read_b128 v[40:43], v10 offset:128
	ds_read_b128 v[44:47], v10 offset:192
	ds_read_u16 v80, v23 offset:0
	ds_read_u16 v81, v23 offset:64
	ds_read_u16 v82, v23 offset:128
	ds_read_u16 v83, v23 offset:192
	s_add_u32 s33, s6, 1
	s_min_u32 s33, s33, 31
	s_add_u32 s36, s6, 2
	s_min_u32 s36, s36, 31
	s_lshl_b32 s7, s33, 14
	s_add_u32 s26, s10, s7
	s_addc_u32 s27, s11, 0
	global_load_dwordx4 v[162:165], v136, s[26:27] offset:0
	global_load_dwordx4 v[166:169], v136, s[26:27] offset:64
	global_load_dwordx4 v[170:173], v136, s[26:27] offset:128
	global_load_dwordx4 v[174:177], v136, s[26:27] offset:192
	s_lshl_b32 s7, s33, 14
	s_add_u32 s28, s12, s7
	s_addc_u32 s29, s13, 0
	global_load_dwordx4 v[178:181], v136, s[28:29] offset:0
	global_load_dwordx4 v[182:185], v136, s[28:29] offset:64
	global_load_dwordx4 v[186:189], v136, s[28:29] offset:128
	global_load_dwordx4 v[190:193], v136, s[28:29] offset:192
	v_readlane_b32 s37, v24, s6
	s_nop 1
	v_mul_f32_e32 v92, s37, v92
	v_mul_f32_e32 v93, s37, v93
	v_mul_f32_e32 v94, s37, v94
	v_mul_f32_e32 v95, s37, v95
	v_mul_f32_e32 v96, s37, v96
	v_mul_f32_e32 v97, s37, v97
	v_mul_f32_e32 v98, s37, v98
	v_mul_f32_e32 v99, s37, v99
	s_waitcnt vmcnt(8)
	s_waitcnt lgkmcnt(7)
	v_mfma_f32_16x16x32_bf16 v[84:87], v[48:51], v[32:35], 0
	s_waitcnt lgkmcnt(6)
	v_mfma_f32_16x16x32_bf16 v[84:87], v[52:55], v[36:39], v[84:87]
	s_waitcnt lgkmcnt(5)
	v_mfma_f32_16x16x32_bf16 v[84:87], v[56:59], v[40:43], v[84:87]
	s_waitcnt lgkmcnt(4)
	v_mfma_f32_16x16x32_bf16 v[84:87], v[60:63], v[44:47], v[84:87]
	s_waitcnt lgkmcnt(0)
	s_nop 4
	v_lshlrev_b32_e32 v80, 16, v80
	v_lshlrev_b32_e32 v81, 16, v81
	v_lshlrev_b32_e32 v82, 16, v82
	v_lshlrev_b32_e32 v83, 16, v83
	v_sub_f32_e32 v26, v80, v84
	v_sub_f32_e32 v27, v81, v85
	v_sub_f32_e32 v28, v82, v86
	v_sub_f32_e32 v29, v83, v87
	v_cvt_pk_bf16_f32 v26, v26, v27
	v_cvt_pk_bf16_f32 v27, v28, v29
	ds_write_b64 v20, v[26:27]
	s_lshl_b32 s7, s33, 14
	s_add_u32 s26, s14, s7
	s_addc_u32 s27, s15, 0
	s_add_i32 m0, s30, 0x14000
	s_nop 0
	global_load_lds_dwordx4 v5, s[26:27]
	s_add_i32 m0, s30, 0x14400
	s_nop 0
	global_load_lds_dwordx4 v6, s[26:27]
	s_lshl_b32 s7, s33, 13
	s_add_u32 s28, s18, s7
	s_addc_u32 s29, s19, 0
	s_add_i32 m0, s31, 0x1a000
	s_nop 0
	global_load_lds_dwordx4 v7, s[28:29]
	s_lshl_b32 s7, s36, 14
	s_add_u32 s26, s24, s7
	s_addc_u32 s27, s25, 0
	s_add_u32 s8, s6, 2
	s_and_b32 s8, s8, 3
	s_lshl_b32 s8, s8, 12
	s_add_u32 s8, s8, s32
	s_add_i32 m0, s8, 0x1f400
	s_nop 0
	global_load_lds_dwordx4 v8, s[26:27]
	s_waitcnt vmcnt(4) lgkmcnt(0)
	s_barrier
	ds_read_b128 v[100:103], v19
	ds_read_b128 v[108:111], v15 offset:0
	ds_read_b128 v[112:115], v15 offset:2048
	ds_read_b128 v[104:107], v19 offset:64
	ds_read_b128 v[116:119], v16 offset:0
	ds_read_b128 v[120:123], v16 offset:2048
	ds_read_b128 v[124:127], v17 offset:0
	ds_read_b128 v[128:131], v18 offset:0
	v_mfma_f32_16x16x32_bf16 v[88:91], v[32:35], v[64:67], 0
	v_mfma_f32_16x16x32_bf16 v[88:91], v[36:39], v[68:71], v[88:91]
	v_mfma_f32_16x16x32_bf16 v[88:91], v[40:43], v[72:75], v[88:91]
	v_mfma_f32_16x16x32_bf16 v[88:91], v[44:47], v[76:79], v[88:91]
	s_waitcnt lgkmcnt(6)
	v_mfma_f32_16x16x32_bf16 v[92:95], v[108:111], v[100:103], v[92:95]
	s_waitcnt lgkmcnt(5)
	v_mfma_f32_16x16x32_bf16 v[96:99], v[112:115], v[100:103], v[96:99]
	s_waitcnt lgkmcnt(3)
	v_mfma_f32_16x16x32_bf16 v[92:95], v[116:119], v[104:107], v[92:95]
	s_waitcnt lgkmcnt(2)
	v_mfma_f32_16x16x32_bf16 v[96:99], v[120:123], v[104:107], v[96:99]
	s_waitcnt lgkmcnt(1)
	v_mfma_f32_16x16x32_bf16 v[88:91], v[100:103], v[124:127], v[88:91]
	s_waitcnt lgkmcnt(0)
	v_mfma_f32_16x16x32_bf16 v[88:91], v[104:107], v[128:131], v[88:91]
	s_lshl_b32 s7, s6, 14
	s_add_u32 s28, s24, s7
	s_addc_u32 s29, s25, 0
	s_nop 1
	v_cvt_pk_bf16_f32 v26, v92, v93
	v_cvt_pk_bf16_f32 v27, v94, v95
	v_cvt_pk_bf16_f32 v28, v96, v97
	v_cvt_pk_bf16_f32 v29, v98, v99
	ds_write_b64 v21, v[26:27]
	ds_write_b64 v21, v[28:29] offset:32
	v_cvt_pk_bf16_f32 v80, v88, v89
	v_cvt_pk_bf16_f32 v81, v90, v91
	global_store_dwordx2 v9, v[80:81], s[28:29]
	s_add_u32 s6, s6, 1
	s_waitcnt vmcnt(13) lgkmcnt(0)
	s_barrier
	s_and_b32 s7, s6, 3
	s_lshl_b32 s7, s7, 12
	v_add_u32_e32 v23, s7, v22
	ds_read_b128 v[32:35], v10 offset:0
	ds_read_b128 v[36:39], v10 offset:64
	ds_read_b128 v[40:43], v10 offset:128
	ds_read_b128 v[44:47], v10 offset:192
	ds_read_u16 v80, v23 offset:0
	ds_read_u16 v81, v23 offset:64
	ds_read_u16 v82, v23 offset:128
	ds_read_u16 v83, v23 offset:192
	s_add_u32 s33, s6, 1
	s_min_u32 s33, s33, 31
	s_add_u32 s36, s6, 2
	s_min_u32 s36, s36, 31
	s_lshl_b32 s7, s33, 14
	s_add_u32 s26, s10, s7
	s_addc_u32 s27, s11, 0
	global_load_dwordx4 v[48:51], v136, s[26:27] offset:0
	global_load_dwordx4 v[52:55], v136, s[26:27] offset:64
	global_load_dwordx4 v[56:59], v136, s[26:27] offset:128
	global_load_dwordx4 v[60:63], v136, s[26:27] offset:192
	s_lshl_b32 s7, s33, 14
	s_add_u32 s28, s12, s7
	s_addc_u32 s29, s13, 0
	global_load_dwordx4 v[64:67], v136, s[28:29] offset:0
	global_load_dwordx4 v[68:71], v136, s[28:29] offset:64
	global_load_dwordx4 v[72:75], v136, s[28:29] offset:128
	global_load_dwordx4 v[76:79], v136, s[28:29] offset:192
	v_readlane_b32 s37, v24, s6
	s_nop 1
	v_mul_f32_e32 v92, s37, v92
	v_mul_f32_e32 v93, s37, v93
	v_mul_f32_e32 v94, s37, v94
	v_mul_f32_e32 v95, s37, v95
	v_mul_f32_e32 v96, s37, v96
	v_mul_f32_e32 v97, s37, v97
	v_mul_f32_e32 v98, s37, v98
	v_mul_f32_e32 v99, s37, v99
	s_waitcnt vmcnt(8)
	s_waitcnt lgkmcnt(7)
	v_mfma_f32_16x16x32_bf16 v[84:87], v[162:165], v[32:35], 0
	s_waitcnt lgkmcnt(6)
	v_mfma_f32_16x16x32_bf16 v[84:87], v[166:169], v[36:39], v[84:87]
	s_waitcnt lgkmcnt(5)
	v_mfma_f32_16x16x32_bf16 v[84:87], v[170:173], v[40:43], v[84:87]
	s_waitcnt lgkmcnt(4)
	v_mfma_f32_16x16x32_bf16 v[84:87], v[174:177], v[44:47], v[84:87]
	s_waitcnt lgkmcnt(0)
	s_nop 4
	v_lshlrev_b32_e32 v80, 16, v80
	v_lshlrev_b32_e32 v81, 16, v81
	v_lshlrev_b32_e32 v82, 16, v82
	v_lshlrev_b32_e32 v83, 16, v83
	v_sub_f32_e32 v26, v80, v84
	v_sub_f32_e32 v27, v81, v85
	v_sub_f32_e32 v28, v82, v86
	v_sub_f32_e32 v29, v83, v87
	v_cvt_pk_bf16_f32 v26, v26, v27
	v_cvt_pk_bf16_f32 v27, v28, v29
	ds_write_b64 v20, v[26:27]
	s_lshl_b32 s7, s33, 14
	s_add_u32 s26, s14, s7
	s_addc_u32 s27, s15, 0
	s_add_i32 m0, s30, 0x10000
	s_nop 0
	global_load_lds_dwordx4 v5, s[26:27]
	s_add_i32 m0, s30, 0x10400
	s_nop 0
	global_load_lds_dwordx4 v6, s[26:27]
	s_lshl_b32 s7, s33, 13
	s_add_u32 s28, s18, s7
	s_addc_u32 s29, s19, 0
	s_add_i32 m0, s31, 0x18000
	s_nop 0
	global_load_lds_dwordx4 v7, s[28:29]
	s_lshl_b32 s7, s36, 14
	s_add_u32 s26, s24, s7
	s_addc_u32 s27, s25, 0
	s_add_u32 s8, s6, 2
	s_and_b32 s8, s8, 3
	s_lshl_b32 s8, s8, 12
	s_add_u32 s8, s8, s32
	s_add_i32 m0, s8, 0x1f400
	s_nop 0
	global_load_lds_dwordx4 v8, s[26:27]
	s_waitcnt vmcnt(4) lgkmcnt(0)
	s_barrier
	ds_read_b128 v[100:103], v19
	ds_read_b128 v[108:111], v15 offset:16384
	ds_read_b128 v[112:115], v15 offset:18432
	ds_read_b128 v[104:107], v19 offset:64
	ds_read_b128 v[116:119], v16 offset:16384
	ds_read_b128 v[120:123], v16 offset:18432
	ds_read_b128 v[124:127], v17 offset:8192
	ds_read_b128 v[128:131], v18 offset:8192
	v_mfma_f32_16x16x32_bf16 v[88:91], v[32:35], v[178:181], 0
	v_mfma_f32_16x16x32_bf16 v[88:91], v[36:39], v[182:185], v[88:91]
	v_mfma_f32_16x16x32_bf16 v[88:91], v[40:43], v[186:189], v[88:91]
	v_mfma_f32_16x16x32_bf16 v[88:91], v[44:47], v[190:193], v[88:91]
	s_waitcnt lgkmcnt(6)
	v_mfma_f32_16x16x32_bf16 v[92:95], v[108:111], v[100:103], v[92:95]
	s_waitcnt lgkmcnt(5)
	v_mfma_f32_16x16x32_bf16 v[96:99], v[112:115], v[100:103], v[96:99]
	s_waitcnt lgkmcnt(3)
	v_mfma_f32_16x16x32_bf16 v[92:95], v[116:119], v[104:107], v[92:95]
	s_waitcnt lgkmcnt(2)
	v_mfma_f32_16x16x32_bf16 v[96:99], v[120:123], v[104:107], v[96:99]
	s_waitcnt lgkmcnt(1)
	v_mfma_f32_16x16x32_bf16 v[88:91], v[100:103], v[124:127], v[88:91]
	s_waitcnt lgkmcnt(0)
	v_mfma_f32_16x16x32_bf16 v[88:91], v[104:107], v[128:131], v[88:91]
	s_lshl_b32 s7, s6, 14
	s_add_u32 s28, s24, s7
	s_addc_u32 s29, s25, 0
	s_nop 1
	v_cvt_pk_bf16_f32 v26, v92, v93
	v_cvt_pk_bf16_f32 v27, v94, v95
	v_cvt_pk_bf16_f32 v28, v96, v97
	v_cvt_pk_bf16_f32 v29, v98, v99
	ds_write_b64 v21, v[26:27]
	ds_write_b64 v21, v[28:29] offset:32
	v_cvt_pk_bf16_f32 v80, v88, v89
	v_cvt_pk_bf16_f32 v81, v90, v91
	global_store_dwordx2 v9, v[80:81], s[28:29]
	s_add_u32 s6, s6, 1
	s_waitcnt vmcnt(13) lgkmcnt(0)
	s_barrier
	s_cmp_lt_u32 s6, 32
	s_cbranch_scc1 .Lscan_loop
	s_lshl_b32 s56, s77, 5
	s_and_b32 s57, s40, 3
	s_lshl_b32 s72, s40, 5
	s_waitcnt vmcnt(0)
	v_readfirstlane_b32 s3, v194
	s_cmp_gt_u32 s3, 63
	s_barrier
	s_cbranch_scc1 .LBB0_421
	s_waitcnt vmcnt(2)
	v_mbcnt_lo_u32_b32 v0, -1, 0
	v_mbcnt_hi_u32_b32 v0, -1, v0
	s_nop 0
	v_cmp_eq_u32_e32 vcc, 0, v0
	s_and_saveexec_b64 s[6:7], vcc
	s_cbranch_execz .LBB0_420
	s_add_i32 s3, 0, 0x23ff0
	v_mov_b32_e32 v0, s3
	s_waitcnt vmcnt(0) expcnt(0) lgkmcnt(0)
	ds_read_b32 v2, v0
	s_add_i32 s3, 0, 0x23ff4
	v_mov_b32_e32 v0, s3
	ds_read_b32 v0, v0
	s_waitcnt lgkmcnt(1)
	v_cmp_ne_u32_e32 vcc, 0, v2
	s_cbranch_vccnz .LBB0_384
	s_mov_b32 s3, 1
	v_mov_b32_e32 v16, 0
	s_branch .LBB0_372
